# same load/finish overlap applied to the two convert_mixer item loops
# speedup vs baseline: 1.0156x; 1.0019x over previous
.LBB0_234:
	s_cmpk_lt_i32 s19, 0x300
	s_cselect_b32 s11, 48, 32
	v_cvt_f32_ubyte0_e32 v35, s11
	v_rcp_iflag_f32_e32 v35, v35
	s_cselect_b32 s5, s97, s77
	s_cselect_b32 s4, s89, s76
	s_cselect_b32 s10, 0, 0xfffffd00
	v_mul_f32_e32 v35, 0x4f7ffffe, v35
	v_cvt_u32_f32_e32 v35, v35
	s_sub_i32 s21, 0, s11
	s_add_i32 s10, s10, s19
	s_abs_i32 s20, s10
	v_readfirstlane_b32 s22, v35
	s_mul_i32 s21, s21, s22
	s_mul_hi_u32 s21, s22, s21
	s_add_i32 s22, s22, s21
	s_mul_hi_u32 s21, s20, s22
	s_mul_i32 s22, s21, s11
	s_sub_i32 s20, s20, s22
	s_ashr_i32 s19, s10, 31
	s_add_i32 s22, s21, 1
	s_sub_i32 s23, s20, s11
	s_cmp_ge_u32 s20, s11
	s_cselect_b32 s21, s22, s21
	s_cselect_b32 s20, s23, s20
	s_add_i32 s22, s21, 1
	s_cmp_ge_u32 s20, s11
	s_cselect_b32 s20, s22, s21
	s_xor_b32 s20, s20, s19
	s_waitcnt lgkmcnt(0)
	s_sub_i32 s20, s20, s19
	ds_read2_b32 v[96:97], v40 offset1:33
	s_mul_i32 s11, s20, s11
	s_waitcnt lgkmcnt(0)
	v_cvt_pk_bf16_f32 v96, v96, v97
	ds_read2_b32 v[98:99], v40 offset0:66 offset1:99
	s_sub_i32 s10, s10, s11
	s_waitcnt lgkmcnt(0)
	v_cvt_pk_bf16_f32 v97, v98, v99
	ds_read2_b32 v[98:99], v40 offset0:132 offset1:165
	s_lshl_b32 s19, s10, 5
	s_waitcnt lgkmcnt(0)
	v_cvt_pk_bf16_f32 v98, v98, v99
	ds_read2_b32 v[100:101], v40 offset0:198 offset1:231
	s_waitcnt lgkmcnt(0)
	v_cvt_pk_bf16_f32 v99, v100, v101
	v_or_b32_e32 v100, s19, v39
	s_lshl_b32 s10, s20, 6
	v_ashrrev_i32_e32 v101, 31, v100
	s_ashr_i32 s11, s10, 31
	v_lshlrev_b64 v[100:101], 11, v[100:101]
	v_lshl_add_u64 v[100:101], s[4:5], 0, v[100:101]
	s_lshl_b64 s[10:11], s[10:11], 1
	v_lshl_add_u64 v[100:101], v[100:101], 0, s[10:11]
	v_mov_b32_e32 v35, v1
	v_lshl_add_u64 v[100:101], v[100:101], 0, v[34:35]
	global_store_dwordx4 v[100:101], v[96:99], off
	ds_read2_b32 v[96:97], v40 offset0:8 offset1:41
	s_and_b64 vcc, exec, s[8:9]
	s_waitcnt lgkmcnt(0)
	v_cvt_pk_bf16_f32 v96, v96, v97
	ds_read2_b32 v[98:99], v40 offset0:74 offset1:107
	s_waitcnt lgkmcnt(0)
	v_cvt_pk_bf16_f32 v97, v98, v99
	ds_read2_b32 v[98:99], v40 offset0:140 offset1:173
	s_waitcnt lgkmcnt(0)
	v_cvt_pk_bf16_f32 v98, v98, v99
	ds_read2_b32 v[100:101], v40 offset0:206 offset1:239
	s_waitcnt lgkmcnt(0)
	v_cvt_pk_bf16_f32 v99, v100, v101
	v_or_b32_e32 v100, s19, v41
	v_ashrrev_i32_e32 v101, 31, v100
	v_lshlrev_b64 v[100:101], 11, v[100:101]
	v_lshl_add_u64 v[100:101], s[4:5], 0, v[100:101]
	v_lshl_add_u64 v[100:101], v[100:101], 0, s[10:11]
	v_lshl_add_u64 v[100:101], v[100:101], 0, v[34:35]
	global_store_dwordx4 v[100:101], v[96:99], off
	ds_read2_b32 v[96:97], v40 offset0:16 offset1:49
	s_waitcnt lgkmcnt(0)
	v_cvt_pk_bf16_f32 v96, v96, v97
	ds_read2_b32 v[98:99], v40 offset0:82 offset1:115
	s_waitcnt lgkmcnt(0)
	v_cvt_pk_bf16_f32 v97, v98, v99
	ds_read2_b32 v[98:99], v40 offset0:148 offset1:181
	s_waitcnt lgkmcnt(0)
	v_cvt_pk_bf16_f32 v98, v98, v99
	ds_read2_b32 v[100:101], v40 offset0:214 offset1:247
	s_waitcnt lgkmcnt(0)
	v_cvt_pk_bf16_f32 v99, v100, v101
	v_or_b32_e32 v100, s19, v42
	v_ashrrev_i32_e32 v101, 31, v100
	v_lshlrev_b64 v[100:101], 11, v[100:101]
	v_lshl_add_u64 v[100:101], s[4:5], 0, v[100:101]
	v_lshl_add_u64 v[100:101], v[100:101], 0, s[10:11]
	v_lshl_add_u64 v[100:101], v[100:101], 0, v[34:35]
	global_store_dwordx4 v[100:101], v[96:99], off
	ds_read2_b32 v[96:97], v40 offset0:24 offset1:57
	s_waitcnt lgkmcnt(0)
	v_cvt_pk_bf16_f32 v96, v96, v97
	ds_read2_b32 v[98:99], v40 offset0:90 offset1:123
	s_waitcnt lgkmcnt(0)
	v_cvt_pk_bf16_f32 v97, v98, v99
	ds_read2_b32 v[98:99], v40 offset0:156 offset1:189
	s_waitcnt lgkmcnt(0)
	v_cvt_pk_bf16_f32 v98, v98, v99
	ds_read2_b32 v[100:101], v40 offset0:222 offset1:255
	s_waitcnt lgkmcnt(0)
	v_cvt_pk_bf16_f32 v99, v100, v101
	v_or_b32_e32 v100, s19, v43
	v_ashrrev_i32_e32 v101, 31, v100
	v_lshlrev_b64 v[100:101], 11, v[100:101]
	v_lshl_add_u64 v[100:101], s[4:5], 0, v[100:101]
	v_lshl_add_u64 v[100:101], v[100:101], 0, s[10:11]
	v_lshl_add_u64 v[100:101], v[100:101], 0, v[34:35]
	global_store_dwordx4 v[100:101], v[96:99], off
	s_waitcnt lgkmcnt(0)
	s_waitcnt vmcnt(35)
	v_mul_f32_e32 v2, v3, v9
	s_waitcnt vmcnt(34)
	v_mul_f32_e32 v3, v8, v10
	s_waitcnt vmcnt(33)
	v_mul_f32_e32 v4, v12, v13
	s_waitcnt vmcnt(32)
	v_mul_f32_e32 v5, v11, v14
	s_waitcnt vmcnt(31)
	v_mul_f32_e32 v6, v16, v17
	s_waitcnt vmcnt(30)
	v_mul_f32_e32 v7, v15, v18
	s_waitcnt vmcnt(29)
	v_mul_f32_e32 v8, v20, v21
	s_waitcnt vmcnt(28)
	v_mul_f32_e32 v9, v19, v22
	s_waitcnt vmcnt(27)
	v_mul_f32_e32 v10, v24, v25
	s_waitcnt vmcnt(26)
	v_mul_f32_e32 v11, v23, v26
	s_waitcnt vmcnt(25)
	v_mul_f32_e32 v12, v28, v29
	s_waitcnt vmcnt(24)
	v_mul_f32_e32 v13, v27, v30
	s_waitcnt vmcnt(23)
	v_mul_f32_e32 v14, v32, v33
	s_waitcnt vmcnt(22)
	v_mul_f32_e32 v15, v31, v94
	s_waitcnt vmcnt(21)
	v_mul_f32_e32 v16, v46, v47
	s_waitcnt vmcnt(20)
	v_mul_f32_e32 v17, v45, v48
	s_waitcnt vmcnt(19)
	v_mul_f32_e32 v18, v50, v51
	s_waitcnt vmcnt(18)
	v_mul_f32_e32 v19, v49, v52
	s_waitcnt vmcnt(17)
	v_mul_f32_e32 v20, v54, v55
	s_waitcnt vmcnt(16)
	v_mul_f32_e32 v21, v53, v56
	s_waitcnt vmcnt(15)
	v_mul_f32_e32 v22, v58, v59
	s_waitcnt vmcnt(14)
	v_mul_f32_e32 v23, v57, v60
	s_waitcnt vmcnt(13)
	v_mul_f32_e32 v24, v62, v63
	s_waitcnt vmcnt(12)
	v_mul_f32_e32 v25, v61, v64
	s_waitcnt vmcnt(11)
	v_mul_f32_e32 v26, v66, v67
	s_waitcnt vmcnt(10)
	v_mul_f32_e32 v27, v65, v68
	s_waitcnt vmcnt(9)
	v_mul_f32_e32 v28, v70, v71
	s_waitcnt vmcnt(8)
	v_mul_f32_e32 v29, v69, v72
	s_waitcnt vmcnt(7)
	v_mul_f32_e32 v30, v74, v75
	s_waitcnt vmcnt(6)
	v_mul_f32_e32 v31, v73, v77
	s_waitcnt vmcnt(5)
	v_mul_f32_e32 v32, v78, v79
	s_waitcnt vmcnt(4)
	v_mul_f32_e32 v33, v76, v80
	s_mov_b32 s19, s18
	s_cbranch_vccnz .LBB0_300

.LBB0_264:
	v_or_b32_e32 v35, 26, v2
	v_mad_i64_i32 v[46:47], s[10:11], v35, s20, 0
	v_lshl_add_u64 v[46:47], v[46:47], 2, v[4:5]
	global_load_dword v94, v[46:47], off nt
	v_mov_b32_e32 v45, 1.0
	s_and_b64 vcc, exec, s[4:5]
	v_mov_b32_e32 v46, 1.0
	s_cbranch_vccnz .LBB0_266
	global_load_dword v46, v[6:7], off offset:112

.LBB0_371:
	s_cmpk_lt_i32 s18, 0xc00
	s_cselect_b32 s11, 0xc0, 32
	v_cvt_f32_ubyte0_e32 v35, s11
	v_rcp_iflag_f32_e32 v35, v35
	s_cselect_b32 s19, 0x400, s95
	s_cselect_b32 s5, s97, s77
	s_cselect_b32 s4, s89, s76
	v_mul_f32_e32 v35, 0x4f7ffffe, v35
	v_cvt_u32_f32_e32 v35, v35
	s_cselect_b32 s10, 0, 0xfffff400
	s_sub_i32 s21, 0, s11
	s_add_i32 s10, s10, s18
	v_readfirstlane_b32 s22, v35
	s_mul_i32 s21, s21, s22
	s_mul_hi_u32 s21, s22, s21
	s_abs_i32 s20, s10
	s_add_i32 s22, s22, s21
	s_mul_hi_u32 s21, s20, s22
	s_mul_i32 s22, s21, s11
	s_sub_i32 s20, s20, s22
	s_ashr_i32 s18, s10, 31
	s_add_i32 s22, s21, 1
	s_sub_i32 s23, s20, s11
	s_cmp_ge_u32 s20, s11
	s_cselect_b32 s21, s22, s21
	s_cselect_b32 s20, s23, s20
	s_add_i32 s22, s21, 1
	s_cmp_ge_u32 s20, s11
	s_cselect_b32 s20, s22, s21
	s_xor_b32 s20, s20, s18
	s_sub_i32 s20, s20, s18
	s_waitcnt lgkmcnt(0)
	s_mul_i32 s11, s20, s11
	ds_read2_b32 v[96:97], v39 offset1:33
	s_sub_i32 s10, s10, s11
	s_waitcnt lgkmcnt(0)
	v_cvt_pk_bf16_f32 v96, v96, v97
	ds_read2_b32 v[98:99], v39 offset0:66 offset1:99
	s_lshl_b32 s18, s10, 5
	s_waitcnt lgkmcnt(0)
	v_cvt_pk_bf16_f32 v97, v98, v99
	ds_read2_b32 v[98:99], v39 offset0:132 offset1:165
	s_lshl_b32 s10, s20, 6
	s_waitcnt lgkmcnt(0)
	v_cvt_pk_bf16_f32 v98, v98, v99
	ds_read2_b32 v[100:101], v39 offset0:198 offset1:231
	v_or_b32_e32 v35, s18, v37
	s_ashr_i32 s11, s10, 31
	s_waitcnt lgkmcnt(0)
	v_cvt_pk_bf16_f32 v99, v100, v101
	v_mad_i64_i32 v[100:101], s[20:21], s19, v35, 0
	v_lshl_add_u64 v[100:101], v[100:101], 1, s[4:5]
	s_lshl_b64 s[10:11], s[10:11], 1
	v_lshl_add_u64 v[100:101], v[100:101], 0, s[10:11]
	v_mov_b32_e32 v35, v1
	v_lshl_add_u64 v[100:101], v[100:101], 0, v[34:35]
	global_store_dwordx4 v[100:101], v[96:99], off
	ds_read2_b32 v[96:97], v39 offset0:8 offset1:41
	s_andn2_b64 vcc, exec, s[8:9]
	s_waitcnt lgkmcnt(0)
	v_cvt_pk_bf16_f32 v96, v96, v97
	ds_read2_b32 v[98:99], v39 offset0:74 offset1:107
	s_waitcnt lgkmcnt(0)
	v_cvt_pk_bf16_f32 v97, v98, v99
	ds_read2_b32 v[98:99], v39 offset0:140 offset1:173
	s_waitcnt lgkmcnt(0)
	v_cvt_pk_bf16_f32 v98, v98, v99
	ds_read2_b32 v[100:101], v39 offset0:206 offset1:239
	s_waitcnt lgkmcnt(0)
	v_cvt_pk_bf16_f32 v99, v100, v101
	v_or_b32_e32 v100, s18, v40
	v_mad_i64_i32 v[100:101], s[20:21], s19, v100, 0
	v_lshl_add_u64 v[100:101], v[100:101], 1, s[4:5]
	v_lshl_add_u64 v[100:101], v[100:101], 0, s[10:11]
	v_lshl_add_u64 v[100:101], v[100:101], 0, v[34:35]
	global_store_dwordx4 v[100:101], v[96:99], off
	ds_read2_b32 v[96:97], v39 offset0:16 offset1:49
	s_waitcnt lgkmcnt(0)
	v_cvt_pk_bf16_f32 v96, v96, v97
	ds_read2_b32 v[98:99], v39 offset0:82 offset1:115
	s_waitcnt lgkmcnt(0)
	v_cvt_pk_bf16_f32 v97, v98, v99
	ds_read2_b32 v[98:99], v39 offset0:148 offset1:181
	s_waitcnt lgkmcnt(0)
	v_cvt_pk_bf16_f32 v98, v98, v99
	ds_read2_b32 v[100:101], v39 offset0:214 offset1:247
	s_waitcnt lgkmcnt(0)
	v_cvt_pk_bf16_f32 v99, v100, v101
	v_or_b32_e32 v100, s18, v41
	v_mad_i64_i32 v[100:101], s[20:21], s19, v100, 0
	v_lshl_add_u64 v[100:101], v[100:101], 1, s[4:5]
	v_lshl_add_u64 v[100:101], v[100:101], 0, s[10:11]
	v_lshl_add_u64 v[100:101], v[100:101], 0, v[34:35]
	global_store_dwordx4 v[100:101], v[96:99], off
	ds_read2_b32 v[96:97], v39 offset0:24 offset1:57
	s_waitcnt lgkmcnt(0)
	v_cvt_pk_bf16_f32 v96, v96, v97
	ds_read2_b32 v[98:99], v39 offset0:90 offset1:123
	s_waitcnt lgkmcnt(0)
	v_cvt_pk_bf16_f32 v97, v98, v99
	ds_read2_b32 v[98:99], v39 offset0:156 offset1:189
	s_waitcnt lgkmcnt(0)
	v_cvt_pk_bf16_f32 v98, v98, v99
	ds_read2_b32 v[100:101], v39 offset0:222 offset1:255
	s_waitcnt lgkmcnt(0)
	v_cvt_pk_bf16_f32 v99, v100, v101
	v_or_b32_e32 v100, s18, v42
	v_mad_i64_i32 v[100:101], s[18:19], s19, v100, 0
	v_lshl_add_u64 v[100:101], v[100:101], 1, s[4:5]
	v_lshl_add_u64 v[100:101], v[100:101], 0, s[10:11]
	v_lshl_add_u64 v[100:101], v[100:101], 0, v[34:35]
	global_store_dwordx4 v[100:101], v[96:99], off
	s_waitcnt lgkmcnt(0)
	s_waitcnt vmcnt(35)
	v_mul_f32_e32 v2, v3, v9
	s_waitcnt vmcnt(34)
	v_mul_f32_e32 v3, v8, v10
	s_waitcnt vmcnt(33)
	v_mul_f32_e32 v4, v12, v13
	s_waitcnt vmcnt(32)
	v_mul_f32_e32 v5, v11, v14
	s_waitcnt vmcnt(31)
	v_mul_f32_e32 v6, v16, v17
	s_waitcnt vmcnt(30)
	v_mul_f32_e32 v7, v15, v18
	s_waitcnt vmcnt(29)
	v_mul_f32_e32 v8, v20, v21
	s_waitcnt vmcnt(28)
	v_mul_f32_e32 v9, v19, v22
	s_waitcnt vmcnt(27)
	v_mul_f32_e32 v10, v24, v25
	s_waitcnt vmcnt(26)
	v_mul_f32_e32 v11, v23, v26
	s_waitcnt vmcnt(25)
	v_mul_f32_e32 v12, v28, v29
	s_waitcnt vmcnt(24)
	v_mul_f32_e32 v13, v27, v30
	s_waitcnt vmcnt(23)
	v_mul_f32_e32 v14, v32, v33
	s_waitcnt vmcnt(22)
	v_mul_f32_e32 v15, v31, v94
	s_waitcnt vmcnt(21)
	v_mul_f32_e32 v16, v45, v46
	s_waitcnt vmcnt(20)
	v_mul_f32_e32 v17, v44, v47
	s_waitcnt vmcnt(19)
	v_mul_f32_e32 v18, v49, v50
	s_waitcnt vmcnt(18)
	v_mul_f32_e32 v19, v48, v51
	s_waitcnt vmcnt(17)
	v_mul_f32_e32 v20, v53, v54
	s_waitcnt vmcnt(16)
	v_mul_f32_e32 v21, v52, v55
	s_waitcnt vmcnt(15)
	v_mul_f32_e32 v22, v57, v58
	s_waitcnt vmcnt(14)
	v_mul_f32_e32 v23, v56, v59
	s_waitcnt vmcnt(13)
	v_mul_f32_e32 v24, v61, v62
	s_waitcnt vmcnt(12)
	v_mul_f32_e32 v25, v60, v63
	s_waitcnt vmcnt(11)
	v_mul_f32_e32 v26, v65, v66
	s_waitcnt vmcnt(10)
	v_mul_f32_e32 v27, v64, v67
	s_waitcnt vmcnt(9)
	v_mul_f32_e32 v28, v69, v70
	s_waitcnt vmcnt(8)
	v_mul_f32_e32 v29, v68, v71
	s_waitcnt vmcnt(7)
	v_mul_f32_e32 v30, v73, v74
	s_waitcnt vmcnt(6)
	v_mul_f32_e32 v31, v72, v76
	s_waitcnt vmcnt(5)
	v_mul_f32_e32 v32, v77, v78
	s_waitcnt vmcnt(4)
	v_mul_f32_e32 v33, v75, v79
	s_mov_b32 s18, s13
	s_cbranch_vccz .LBB0_437

.LBB0_401:
	v_or_b32_e32 v35, 26, v2
	v_mad_i64_i32 v[44:45], s[10:11], v35, s19, 0
	v_lshl_add_u64 v[44:45], v[44:45], 2, v[4:5]
	global_load_dword v94, v[44:45], off nt
	v_mov_b32_e32 v44, 1.0
	s_and_b64 vcc, exec, s[4:5]
	v_mov_b32_e32 v45, 1.0
	s_cbranch_vccnz .LBB0_403
	global_load_dword v45, v[6:7], off offset:112
